# v070 + GEMM1 tile group size 4 + nt on attention B-item K/V loads
# baseline (speedup 1.0000x reference)
;     __device__ __forceinline__ bool next(int i, Unit& u) const { const long L = (long)i * G + c; if (L >= nwg) return false; tile_of((int)L, nM, nN, u.pm, u.pn); u.k0 = 0; u.nt = nt; u.part = 0; return true; }
;     __device__ __forceinline__ bool next(int i, Unit& u) const { const long L = (long)i * G + c; if (L >= nwg) return false; int j; tile_of((int)L, nM, nN, u.pm, j); u.pn = list[j]; u.k0 = 0; u.nt = nt; u.part = 0; return true; }
; template <class Epi, class Sched, bool FP8 = false>
; __device__ __forceinline__ void gemm_phase(LAS unsigned char* lds, const Gemm g, const Sched& S, const Epi& E) {
;     ...
;     if (!S.next(0, cur)) return;
.LBB0_62:
	s_or_b64 exec, exec, s[4:5]
	s_load_dword s46, s[70:71], 0x1c4
	s_add_u32 s96, s90, 0x9000000
	s_addc_u32 s97, s91, 0
	s_barrier
	s_waitcnt lgkmcnt(0)
	s_cmp_lt_i32 s46, 1
	s_cbranch_scc1 .LBB0_267
	s_lshl_b32 s16, s46, 6
	s_cmp_lt_i32 s2, s16
	s_cselect_b64 s[4:5], -1, 0
	s_cmp_ge_i32 s2, s16
	v_readfirstlane_b32 s24, v160
	s_cbranch_scc1 .LBB0_65
	s_lshl_b32 s7, s46, 2
	s_abs_i32 s8, s7
	v_cvt_f32_u32_e32 v0, s8
	s_lshr_b32 s1, s3, 29
	s_add_i32 s1, s2, s1
	s_and_b32 s6, s1, -8
	v_rcp_iflag_f32_e32 v0, v0
	s_lshl_b32 s0, s46, 3
	s_sub_i32 s6, s2, s6
	s_and_b32 s0, s0, 0x1ffffff8
	v_mul_f32_e32 v0, 0x4f7ffffe, v0
	v_cvt_u32_f32_e32 v0, v0
	s_lshr_b32 s9, s6, 31
	s_or_b32 s0, s0, s9
	s_sub_i32 s9, 0, s8
	v_readfirstlane_b32 s10, v0
	s_mul_i32 s0, s0, s6
	s_ashr_i32 s1, s1, 3
	s_mul_i32 s9, s9, s10
	s_add_i32 s0, s0, s1
	s_mul_hi_u32 s9, s10, s9
	s_abs_i32 s6, s0
	s_add_i32 s10, s10, s9
	s_mul_hi_u32 s9, s6, s10
	s_mul_i32 s10, s9, s8
	s_xor_b32 s1, s0, s7
	s_sub_i32 s6, s6, s10
	s_ashr_i32 s1, s1, 31
	s_add_i32 s10, s9, 1
	s_sub_i32 s11, s6, s8
	s_cmp_ge_u32 s6, s8
	s_cselect_b32 s9, s10, s9
	s_cselect_b32 s6, s11, s6
	s_add_i32 s10, s9, 1
	s_cmp_ge_u32 s6, s8
	s_cselect_b32 s6, s10, s9
	s_xor_b32 s6, s6, s1
	s_sub_i32 s1, s6, s1
	s_lshl_b32 s6, s1, 2
	s_sub_i32 s8, 64, s6
	s_min_i32 s8, s8, 4
	s_abs_i32 s9, s8
	v_cvt_f32_u32_e32 v0, s9
	s_sub_i32 s10, 0, s9
	s_mul_i32 s1, s1, s7
	s_sub_i32 s0, s0, s1
	v_rcp_iflag_f32_e32 v0, v0
	s_abs_i32 s7, s0
	s_xor_b32 s1, s0, s8
	s_ashr_i32 s1, s1, 31
	v_mul_f32_e32 v0, 0x4f7ffffe, v0
	v_cvt_u32_f32_e32 v0, v0
	s_nop 0
	v_readfirstlane_b32 s11, v0
	s_mul_i32 s10, s10, s11
	s_mul_hi_u32 s10, s11, s10
	s_add_i32 s11, s11, s10
	s_mul_hi_u32 s10, s7, s11
	s_mul_i32 s11, s10, s9
	s_sub_i32 s7, s7, s11
	s_add_i32 s11, s10, 1
	s_sub_i32 s17, s7, s9
	s_cmp_ge_u32 s7, s9
	s_cselect_b32 s10, s11, s10
	s_cselect_b32 s7, s17, s7
	s_add_i32 s11, s10, 1
	s_cmp_ge_u32 s7, s9
	s_cselect_b32 s7, s11, s10
	s_xor_b32 s7, s7, s1
	s_sub_i32 s1, s7, s1
	s_mul_i32 s7, s1, s8
	s_sub_i32 s0, s0, s7
	s_add_i32 s8, s0, s6
	s_ashr_i32 s6, s1, 31
	s_add_u32 s0, s70, s1
	s_addc_u32 s1, s71, s6
	v_mov_b32_e32 v0, 0
	global_load_ubyte v0, v0, s[0:1] offset:400
	s_waitcnt vmcnt(0)
	v_readfirstlane_b32 s0, v0

;     __device__ __forceinline__ bool next(int i, Unit& u) const { const long L = (long)i * G + c; if (L >= nwg) return false; tile_of((int)L, nM, nN, u.pm, u.pn); u.k0 = 0; u.nt = nt; u.part = 0; return true; }
;     __device__ __forceinline__ bool next(int i, Unit& u) const { const long L = (long)i * G + c; if (L >= nwg) return false; int j; tile_of((int)L, nM, nN, u.pm, j); u.pn = list[j]; u.k0 = 0; u.nt = nt; u.part = 0; return true; }
; #define PG8_STAGE(bufoff, gbase, voff) do { _Pragma("unroll") for (int _i = 0; _i < 2; ++_i) \
;         __builtin_amdgcn_global_load_lds((const unsigned*)((const char*)(gbase) + (voff)[_i]), (LAS unsigned*)(lds + (bufoff) + ldsw + _i * 8192), 16, 0, 0); } while (0)
; #define PG8_WAIT_V(n) asm volatile("s_waitcnt vmcnt(" #n ")" ::: "memory")
; #define PG8_BAR __builtin_amdgcn_s_barrier()
; template <class Epi, class Sched, bool FP8 = false>
; __device__ __forceinline__ void gemm_phase(LAS unsigned char* lds, const Gemm g, const Sched& S, const Epi& E) {
;     ...
;     const char* cA = (const char*)g.A + (size_t)cur.pm * tstepA + (size_t)cur.k0 * 2; const char* cB = (const char*)g.Bt + (size_t)cur.pn * tstepB + (size_t)cur.k0 * 2;
;     PG8_STAGE(PG8_SB(0, 0), cB, voffB); PG8_STAGE(PG8_SB(0, 1), cB + hstepB, voffB); PG8_STAGE(PG8_SA(0, 0), cA, voffA); PG8_STAGE(PG8_SA(0, 1), cA + hstepA, voffA);
;     if (wr == 1) PG8_BAR;
;     PG8_WAIT_V(2); PG8_BAR;
;     PG8_STAGE(PG8_SB(1, 0), cB + kstep, voffB); PG8_STAGE(PG8_SA(1, 0), cA + kstep, voffA); PG8_STAGE(PG8_SB(1, 1), cB + hstepB + kstep, voffB);
;     PG8_WAIT_V(6); PG8_BAR;
;     for (;;) {
;         const bool has_next = S.next(ui + 1, nxt);
;         const char* nA = has_next ? (const char*)g.A + (size_t)nxt.pm * tstepA + (size_t)nxt.k0 * 2 : cA; const char* nB = has_next ? (const char*)g.Bt + (size_t)nxt.pn * tstepB + (size_t)nxt.k0 * 2 : cB;
.LBB0_68:
	s_mov_b64 s[22:23], 0x80
	s_and_b32 s1, s4, 3
	s_add_i32 m0, s48, 0x18000
	v_lshl_add_u64 v[6:7], v[6:7], 0, s[22:23]
	s_lshl_b32 s9, s5, 13
	s_lshl_b32 s52, s1, 5
	s_lshl_b32 s30, s1, 12
	s_waitcnt vmcnt(2)
	s_barrier
	global_load_lds_dwordx4 v[6:7], off
	v_lshl_add_u64 v[4:5], v[4:5], 0, s[22:23]
	s_add_i32 m0, s48, 0x1a000
	s_add_i32 s53, s48, 0x8000
	s_add_i32 s54, s48, 0xa000
	global_load_lds_dwordx4 v[4:5], off
	v_lshl_add_u64 v[0:1], v[0:1], 0, s[22:23]
	s_mov_b32 m0, s53
	s_add_u32 s26, s10, 0x80080
	global_load_lds_dwordx4 v[0:1], off
	v_lshl_add_u64 v[0:1], v[2:3], 0, s[22:23]
	s_mov_b32 m0, s54
	s_addc_u32 s27, s11, 0
	global_load_lds_dwordx4 v[0:1], off
	s_add_i32 m0, s48, 0x1c000
	v_lshl_add_u64 v[0:1], s[26:27], 0, v[168:169]
	global_load_lds_dwordx4 v[0:1], off
	v_lshl_add_u64 v[0:1], s[26:27], 0, v[172:173]
	s_add_i32 m0, s48, 0x1e000
	s_cmpk_lt_u32 s24, 0x100
	global_load_lds_dwordx4 v[0:1], off
	v_and_b32_e32 v0, 15, v160
	s_cselect_b64 s[24:25], -1, 0
	s_lshl_b32 s55, s1, 6
	v_lshl_or_b32 v161, s5, 6, v0
	s_or_b32 s5, s55, s52
	s_and_b32 s56, s5, 0xa0
	s_cmp_lt_u32 s1, 2
	s_cselect_b64 s[26:27], -1, 0
	s_lshl_b32 s1, s4, 8
	s_and_b32 s1, s1, 0x100
	s_add_u32 s1, s90, s1
	s_addc_u32 s4, s91, 0
	s_add_u32 s28, s1, 0x7c00000
	s_addc_u32 s29, s4, 0
	s_lshl_b32 s57, s46, 2
	s_abs_i32 s58, s57
	v_cvt_f32_u32_e32 v3, s58
	v_lshlrev_b32_e32 v1, 1, v164
	v_lshlrev_b32_e32 v2, 2, v160
	v_lshlrev_b32_e32 v4, 6, v160
	v_rcp_iflag_f32_e32 v3, v3
	s_movk_i32 s1, 0x3c0
	v_lshl_or_b32 v0, v0, 6, v1
	v_and_b32_e32 v2, 32, v2
	v_and_or_b32 v1, v4, s1, v1
	v_bitop3_b32 v163, s30, v1, v2 bitop3:0xf6
	v_mul_f32_e32 v1, 0x4f7ffffe, v3
	v_cvt_u32_f32_e32 v1, v1
	v_bitop3_b32 v0, v0, s9, v2 bitop3:0xde
	v_lshlrev_b32_e32 v2, 11, v10
	s_sub_i32 s1, 0, s58
	v_readfirstlane_b32 s4, v1
	v_lshlrev_b32_e32 v1, 8, v160
	v_and_b32_e32 v1, 0x38000, v1
	v_or3_b32 v1, v8, v1, v2
	v_add_u32_e32 v176, v1, v9
	v_lshlrev_b32_e32 v1, 4, v11
	s_waitcnt vmcnt(6)
	s_mul_i32 s1, s1, s4
	v_and_b32_e32 v1, 0x78000, v1
	s_mul_hi_u32 s1, s4, s1
	v_or3_b32 v1, v8, v1, v2
	s_add_i32 s62, 0, 0x10000
	s_add_i32 s63, 0, 0x14000
	s_lshl_b32 s59, s46, 3
	s_bfe_i32 s60, s46, 0x1001e
	s_add_i32 s61, s4, s1
	v_mov_b32_e32 v177, v175
	v_add_u32_e32 v178, v1, v9
	v_mov_b32_e32 v179, v175
	v_mov_b64_e32 v[180:181], s[16:17]
	v_add_u32_e32 v165, s62, v163
	v_add_u32_e32 v193, s63, v163
	v_add_u32_e32 v194, 0, v0
	v_mov_b32_e32 v195, 0x7f7f7f7f
	s_mov_b32 s30, 0x3c800000
	s_movk_i32 s64, 0x2500
	s_movk_i32 s65, 0x1b00
	s_movk_i32 s66, 0x5a00
	v_lshlrev_b32_e32 v182, 3, v164
	v_mov_b32_e32 v196, 0x3c800000
	v_mov_b32_e32 v197, 0x3b0293ee
	v_mov_b32_e32 v198, 0x3b38aa3b
	s_mov_b32 s67, 0
	s_barrier
	s_branch .LBB0_71

.LBB0_71:
	s_add_i32 s67, s67, 1
	s_mul_i32 s1, s67, s93
	s_mul_hi_u32 s4, s67, s92
	s_add_i32 s4, s4, s1
	s_mul_i32 s1, s67, s92
	s_add_u32 s38, s1, s2
	s_addc_u32 s39, s4, s3
	v_cmp_ge_i64_e32 vcc, s[38:39], v[180:181]
	v_cmp_lt_i64_e64 s[4:5], s[38:39], v[180:181]
	s_cbranch_vccnz .LBB0_73
	s_ashr_i32 s1, s38, 31
	s_lshr_b32 s1, s1, 29
	s_add_i32 s1, s38, s1
	s_ashr_i32 s9, s1, 3
	s_and_b32 s1, s1, -8
	s_sub_i32 s1, s38, s1
	s_lshr_b32 s16, s1, 31
	s_or_b32 s16, s59, s16
	s_mul_i32 s1, s1, s16
	s_add_i32 s1, s1, s9
	s_abs_i32 s16, s1
	s_mul_hi_u32 s33, s16, s61
	s_mul_i32 s34, s33, s58
	s_ashr_i32 s9, s1, 31
	s_sub_i32 s16, s16, s34
	s_xor_b32 s9, s9, s60
	s_add_i32 s34, s33, 1
	s_sub_i32 s35, s16, s58
	s_cmp_ge_u32 s16, s58
	s_cselect_b32 s33, s34, s33
	s_cselect_b32 s16, s35, s16
	s_add_i32 s34, s33, 1
	s_cmp_ge_u32 s16, s58
	s_cselect_b32 s16, s34, s33
	s_xor_b32 s16, s16, s9
	s_sub_i32 s9, s16, s9
	s_lshl_b32 s16, s9, 2
	s_sub_i32 s33, 64, s16
	s_min_i32 s33, s33, 4
	s_abs_i32 s34, s33
	v_cvt_f32_u32_e32 v0, s34
	s_sub_i32 s36, 0, s34
	s_mul_i32 s9, s9, s57
	s_sub_i32 s1, s1, s9
	v_rcp_iflag_f32_e32 v0, v0
	s_abs_i32 s35, s1
	s_xor_b32 s9, s1, s33
	s_ashr_i32 s9, s9, 31
	v_mul_f32_e32 v0, 0x4f7ffffe, v0
	v_cvt_u32_f32_e32 v0, v0
	s_nop 0
	v_readfirstlane_b32 s37, v0
	s_mul_i32 s36, s36, s37
	s_mul_hi_u32 s36, s37, s36
	s_add_i32 s37, s37, s36
	s_mul_hi_u32 s36, s35, s37
	s_mul_i32 s37, s36, s34
	s_sub_i32 s35, s35, s37
	s_add_i32 s37, s36, 1
	s_sub_i32 s38, s35, s34
	s_cmp_ge_u32 s35, s34
	s_cselect_b32 s36, s37, s36
	s_cselect_b32 s35, s38, s35
	s_add_i32 s37, s36, 1
	s_cmp_ge_u32 s35, s34
	s_cselect_b32 s34, s37, s36
	s_xor_b32 s34, s34, s9
	s_sub_i32 s9, s34, s9
	s_mul_i32 s33, s9, s33
	s_sub_i32 s1, s1, s33
	s_add_i32 s34, s1, s16
	s_and_b32 s1, s9, -4
	s_add_u32 s1, s1, 0x190
	s_load_dword s36, s[70:71], s1
	s_and_b32 s37, s9, 3
	s_lshl_b32 s37, s37, 3
	s_waitcnt lgkmcnt(0)
	s_lshr_b32 s36, s36, s37
	s_and_b32 s36, s36, 0xff

; #define LAS __attribute__((address_space(3)))
; template <int DH>
; __device__ __forceinline__ void load_kv(LAS unsigned char* Kl, LAS unsigned char* Vl, const bf16_t* Hk, const bf16_t* Hv, long tok0, int tstride, int jlo, int tid) {
;     ...
;     for (int c = 0; c < PER; ++c) { const int idx = c * 512 + tid, row = idx / CPR, ch = idx % CPR;
;         if (row >= jlo) { const size_t off = (size_t)(tok0 + (long)row * tstride) * DIN + ch * 8; kv[c] = *(const u32x4*)(Hk + off); vv[c] = *(const u32x4*)(Hv + off); }
;         else { kv[c] = (u32x4){0u, 0u, 0u, 0u}; vv[c] = (u32x4){0u, 0u, 0u, 0u}; } }
; __global__ void __launch_bounds__(512, 2) hybrid_fwd(Args a) {
;     ...
;                 const int bi = it - N_A, grp = bi >> 9, rem = bi & 511, hs = rem >> 7, rb = rem & 127;
;                 const int dsh = 2 * grp, d = 1 << dsh;
;                 const int nblk = 128 >> dsh, r = rb / nblk, b = rb % nblk;
;                 LAS unsigned char* Kl = lds; LAS unsigned char* Vl = lds + 256 * 288;
;                 const int jlo = (b == 0) ? 128 : 0;
;                 const int colh = grp * 512 + hs * 128;
;                 load_kv<128>(Kl, Vl, H + OFF_KB + colh, H + OFF_VB + colh, ((long)(b - 1) * 128) * d + r, d, jlo, tid);
.LBB0_310:
	s_or_b64 exec, exec, s[14:15]
	s_movk_i32 s14, 0xff
	v_cmp_lt_i32_e32 vcc, s14, v1
	s_barrier
	s_and_saveexec_b64 s[14:15], vcc
	s_xor_b64 s[86:87], exec, s[14:15]
	s_cbranch_execz .LBB0_328
	v_add_u32_e32 v2, 0xffffff00, v1
	v_lshrrev_b32_e32 v148, 9, v2
	v_lshlrev_b32_e32 v147, 1, v148
	s_movk_i32 s14, 0x80
	v_and_b32_e32 v0, 0x7f, v1
	v_lshrrev_b32_e64 v3, v147, s14
	v_sub_u32_e32 v4, 7, v147
	v_lshrrev_b32_e32 v154, v4, v0
	v_add_u32_e32 v0, -1, v3
	s_movk_i32 s14, 0x7f
	v_bitop3_b32 v149, v0, v1, s14 bitop3:0x80
	v_bfe_u32 v222, v2, 7, 2
	v_subrev_co_u32_e32 v0, vcc, 1, v149
	v_lshlrev_b32_e32 v150, 7, v222
	s_movk_i32 s14, 0xfe00
	v_ashrrev_i32_e32 v1, 31, v0
	v_and_or_b32 v152, v2, s14, v150
	v_mov_b32_e32 v153, v8
	v_lshlrev_b64 v[0:1], 7, v[0:1]
	v_mov_b32_e32 v96, 0
	v_cndmask_b32_e32 v223, 0, v219, vcc
	v_lshlrev_b64 v[2:3], 1, v[152:153]
	v_lshlrev_b64 v[166:167], v147, v[0:1]
	v_lshl_add_u64 v[158:159], s[4:5], 0, v[2:3]
	v_lshl_add_u64 v[164:165], s[8:9], 0, v[2:3]
	v_or_b32_e32 v166, v166, v154
	v_cmp_ge_u32_e32 vcc, v112, v223
	v_mov_b32_e32 v97, v96
	v_mov_b32_e32 v98, v96
	v_mov_b32_e32 v99, v96
	v_mov_b32_e32 v0, v96
	v_mov_b32_e32 v1, v96
	v_mov_b32_e32 v2, v96
	v_mov_b32_e32 v3, v96
	s_and_saveexec_b64 s[14:15], vcc
	s_cbranch_execz .LBB0_313
	v_lshlrev_b64 v[0:1], v147, v[112:113]
	v_lshl_add_u64 v[0:1], v[166:167], 0, v[0:1]
	v_mad_u64_u32 v[2:3], s[16:17], v0, s19, 0
	v_mov_b32_e32 v0, v3
	v_mad_u64_u32 v[0:1], s[16:17], v1, s19, v[0:1]
	v_or_b32_e32 v2, v2, v110
	v_mov_b32_e32 v3, v0
	v_lshlrev_b64 v[0:1], 1, v[2:3]
	v_lshl_add_u64 v[2:3], v[158:159], 0, v[0:1]
	v_lshl_add_u64 v[4:5], v[164:165], 0, v[0:1]
	global_load_dwordx4 v[0:3], v[2:3], off nt
	s_nop 0
	global_load_dwordx4 v[96:99], v[4:5], off nt
.LBB0_313:
	s_or_b64 exec, exec, s[14:15]
	v_cmp_ge_u32_e32 vcc, v114, v223
	s_and_saveexec_b64 s[14:15], vcc
	s_xor_b64 s[14:15], exec, s[14:15]
	s_cbranch_execz .LBB0_315
	v_lshlrev_b64 v[4:5], v147, v[114:115]
	v_lshl_add_u64 v[4:5], v[166:167], 0, v[4:5]
	v_mad_u64_u32 v[6:7], s[16:17], v4, s19, 0
	v_mov_b32_e32 v4, v7
	v_mad_u64_u32 v[4:5], s[16:17], v5, s19, v[4:5]
	v_or_b32_e32 v6, v6, v110
	v_mov_b32_e32 v7, v4
	v_lshlrev_b64 v[10:11], 1, v[6:7]
	v_lshl_add_u64 v[4:5], v[158:159], 0, v[10:11]
	global_load_dwordx4 v[4:7], v[4:5], off nt
	v_lshl_add_u64 v[10:11], v[164:165], 0, v[10:11]
	global_load_dwordx4 v[100:103], v[10:11], off nt
	v_mov_b32_e32 v9, v8
	v_mov_b32_e32 v10, v8
	v_mov_b32_e32 v11, v8
	s_waitcnt vmcnt(1)
	v_mov_b64_e32 v[62:63], v[30:31]
	v_mov_b32_e32 v64, v0
	v_mov_b32_e32 v65, v1
	v_mov_b32_e32 v66, v2
	v_mov_b32_e32 v67, v3
	v_mov_b32_e32 v72, v8
	v_mov_b32_e32 v73, v8
	v_mov_b32_e32 v74, v8
	v_mov_b32_e32 v75, v8
	v_mov_b32_e32 v76, v8
	v_mov_b32_e32 v77, v8
	v_mov_b32_e32 v78, v8
	v_mov_b32_e32 v79, v8
	v_mov_b64_e32 v[42:43], v[10:11]
	v_mov_b64_e32 v[40:41], v[8:9]
	v_mov_b64_e32 v[34:35], v[2:3]
	v_mov_b64_e32 v[32:33], v[0:1]
	v_mov_b64_e32 v[60:61], v[28:29]
	v_mov_b64_e32 v[58:59], v[26:27]
	v_mov_b64_e32 v[56:57], v[24:25]
	v_mov_b64_e32 v[54:55], v[22:23]
	v_mov_b64_e32 v[52:53], v[20:21]
	v_mov_b64_e32 v[50:51], v[18:19]
	v_mov_b64_e32 v[48:49], v[16:17]
	v_mov_b64_e32 v[46:47], v[14:15]
	v_mov_b64_e32 v[44:45], v[12:13]
	v_mov_b32_e32 v68, v4
	v_mov_b32_e32 v69, v5
	v_mov_b32_e32 v70, v6
	v_mov_b32_e32 v71, v7
	v_mov_b64_e32 v[38:39], v[6:7]
	v_mov_b64_e32 v[36:37], v[4:5]

; template <int DH>
; __device__ __forceinline__ void load_kv(LAS unsigned char* Kl, LAS unsigned char* Vl, const bf16_t* Hk, const bf16_t* Hv, long tok0, int tstride, int jlo, int tid) {
;     ...
;     for (int c = 0; c < PER; ++c) { const int idx = c * 512 + tid, row = idx / CPR, ch = idx % CPR;
;         if (row >= jlo) { const size_t off = (size_t)(tok0 + (long)row * tstride) * DIN + ch * 8; kv[c] = *(const u32x4*)(Hk + off); vv[c] = *(const u32x4*)(Hv + off); }
;         else { kv[c] = (u32x4){0u, 0u, 0u, 0u}; vv[c] = (u32x4){0u, 0u, 0u, 0u}; } }
.LBB0_317:
	s_or_b64 exec, exec, s[14:15]
	v_cmp_ge_u32_e32 vcc, v116, v223
	s_and_saveexec_b64 s[14:15], vcc
	s_xor_b64 s[14:15], exec, s[14:15]
	s_cbranch_execz .LBB0_319
	v_lshlrev_b64 v[32:33], v147, v[116:117]
	v_lshl_add_u64 v[32:33], v[166:167], 0, v[32:33]
	v_mad_u64_u32 v[34:35], s[16:17], v32, s19, 0
	v_mov_b32_e32 v32, v35
	v_mad_u64_u32 v[32:33], s[16:17], v33, s19, v[32:33]
	v_or_b32_e32 v34, v34, v110
	v_mov_b32_e32 v35, v32
	v_lshlrev_b64 v[32:33], 1, v[34:35]
	v_lshl_add_u64 v[34:35], v[158:159], 0, v[32:33]
	global_load_dwordx4 v[72:75], v[34:35], off nt
	v_lshl_add_u64 v[32:33], v[164:165], 0, v[32:33]
	global_load_dwordx4 v[104:107], v[32:33], off nt
	s_waitcnt vmcnt(3)
	v_mov_b64_e32 v[62:63], v[30:31]
	v_mov_b64_e32 v[42:43], v[10:11]
	v_mov_b64_e32 v[40:41], v[8:9]
	v_mov_b64_e32 v[38:39], v[6:7]
	v_mov_b64_e32 v[36:37], v[4:5]
	v_mov_b64_e32 v[34:35], v[2:3]
	v_mov_b64_e32 v[32:33], v[0:1]
	v_mov_b32_e32 v64, v0
	v_mov_b32_e32 v65, v1
	v_mov_b32_e32 v66, v2
	v_mov_b32_e32 v67, v3
	v_mov_b32_e32 v68, v4
	v_mov_b32_e32 v69, v5
	v_mov_b32_e32 v70, v6
	v_mov_b32_e32 v71, v7
	v_mov_b32_e32 v76, v8
	v_mov_b32_e32 v77, v8
	v_mov_b32_e32 v78, v8
	v_mov_b32_e32 v79, v8
	v_mov_b64_e32 v[60:61], v[28:29]
	v_mov_b64_e32 v[58:59], v[26:27]
	v_mov_b64_e32 v[56:57], v[24:25]
	v_mov_b64_e32 v[54:55], v[22:23]
	v_mov_b64_e32 v[52:53], v[20:21]
	v_mov_b64_e32 v[50:51], v[18:19]
	v_mov_b64_e32 v[48:49], v[16:17]
	v_mov_b64_e32 v[46:47], v[14:15]
	v_mov_b64_e32 v[44:45], v[12:13]
	s_waitcnt vmcnt(1)
	v_mov_b32_e32 v40, v72
	v_mov_b32_e32 v41, v73
	v_mov_b32_e32 v42, v74
	v_mov_b32_e32 v43, v75

; template <int DH>
; __device__ __forceinline__ void load_kv(LAS unsigned char* Kl, LAS unsigned char* Vl, const bf16_t* Hk, const bf16_t* Hv, long tok0, int tstride, int jlo, int tid) {
;     ...
;     for (int c = 0; c < PER; ++c) { const int idx = c * 512 + tid, row = idx / CPR, ch = idx % CPR;
;         if (row >= jlo) { const size_t off = (size_t)(tok0 + (long)row * tstride) * DIN + ch * 8; kv[c] = *(const u32x4*)(Hk + off); vv[c] = *(const u32x4*)(Hv + off); }
;         else { kv[c] = (u32x4){0u, 0u, 0u, 0u}; vv[c] = (u32x4){0u, 0u, 0u, 0u}; } }
.LBB0_321:
	s_or_b64 exec, exec, s[14:15]
	v_cmp_ge_u32_e32 vcc, v118, v223
	s_and_saveexec_b64 s[14:15], vcc
	s_xor_b64 s[14:15], exec, s[14:15]
	s_cbranch_execz .LBB0_323
	s_waitcnt vmcnt(1)
	v_lshlrev_b64 v[0:1], v147, v[118:119]
	v_lshl_add_u64 v[0:1], v[166:167], 0, v[0:1]
	v_mad_u64_u32 v[2:3], s[16:17], v0, s19, 0
	v_mov_b32_e32 v0, v3
	v_mad_u64_u32 v[0:1], s[16:17], v1, s19, v[0:1]
	v_or_b32_e32 v2, v2, v110
	v_mov_b32_e32 v3, v0
	v_lshlrev_b64 v[0:1], 1, v[2:3]
	v_lshl_add_u64 v[2:3], v[158:159], 0, v[0:1]
	v_lshl_add_u64 v[0:1], v[164:165], 0, v[0:1]
	global_load_dwordx4 v[44:47], v[2:3], off nt
	s_nop 0
	global_load_dwordx4 v[0:3], v[0:1], off nt

; #define LAS __attribute__((address_space(3)))
; template <int DH>
; __device__ __forceinline__ void load_kv(LAS unsigned char* Kl, LAS unsigned char* Vl, const bf16_t* Hk, const bf16_t* Hv, long tok0, int tstride, int jlo, int tid) {
;     ...
;     for (int c = 0; c < PER; ++c) { const int idx = c * 512 + tid, row = idx / CPR, ch = idx % CPR;
;         if (row >= jlo) { const size_t off = (size_t)(tok0 + (long)row * tstride) * DIN + ch * 8; kv[c] = *(const u32x4*)(Hk + off); vv[c] = *(const u32x4*)(Hv + off); }
;         else { kv[c] = (u32x4){0u, 0u, 0u, 0u}; vv[c] = (u32x4){0u, 0u, 0u, 0u}; } }
; #pragma unroll
;     for (int c = 0; c < PER; ++c) { const int idx = c * 512 + tid, row = idx / CPR, ch = idx % CPR;
;         *(LAS u32x4*)(Kl + row * KS + ch * 16) = kv[c]; *(LAS u32x4*)(Vl + row * VS + ch * 16) = vv[c]; }
; __global__ void __launch_bounds__(512, 2) hybrid_fwd(Args a) {
;     ...
;                 const size_t tok = ((size_t)b * 128 + wave * 16 + (lane & 15)) * d + r;
;                 const bf16_t* qrow = H + tok * DIN + OFF_QB + colh;
;                 bf16x8 qb4[4]; u32x2 gdum[8];
; #pragma unroll
;                 for (int ks = 0; ks < 4; ++ks) qb4[ks] = *(const bf16x8*)(qrow + ks * 32 + 8 * (lane >> 4));
.LBB0_325:
	s_or_b64 exec, exec, s[14:15]
	v_lshlrev_b64 v[4:5], v147, v[120:121]
	v_lshlrev_b64 v[14:15], v147, v[122:123]
	v_lshl_add_u64 v[4:5], v[166:167], 0, v[4:5]
	v_lshl_add_u64 v[14:15], v[166:167], 0, v[14:15]
	v_mad_u64_u32 v[6:7], s[14:15], v4, s19, 0
	v_mad_u64_u32 v[16:17], s[14:15], v14, s19, 0
	v_lshlrev_b64 v[22:23], v147, v[124:125]
	v_lshlrev_b64 v[30:31], v147, v[126:127]
	v_mov_b32_e32 v4, v7
	v_mov_b32_e32 v14, v17
	v_lshl_add_u64 v[22:23], v[166:167], 0, v[22:23]
	v_lshl_add_u64 v[30:31], v[166:167], 0, v[30:31]
	v_mad_u64_u32 v[4:5], s[14:15], v5, s19, v[4:5]
	v_mad_u64_u32 v[14:15], s[14:15], v15, s19, v[14:15]
	v_mad_u64_u32 v[24:25], s[14:15], v22, s19, 0
	v_mad_u64_u32 v[48:49], s[14:15], v30, s19, 0
	v_or_b32_e32 v6, v6, v110
	v_mov_b32_e32 v7, v4
	v_or_b32_e32 v16, v16, v110
	v_mov_b32_e32 v17, v14
	v_mov_b32_e32 v22, v25
	v_mov_b32_e32 v30, v49
	v_lshlrev_b64 v[10:11], 1, v[6:7]
	v_lshlrev_b64 v[18:19], 1, v[16:17]
	v_mad_u64_u32 v[22:23], s[14:15], v23, s19, v[22:23]
	v_mad_u64_u32 v[30:31], s[14:15], v31, s19, v[30:31]
	v_lshl_add_u64 v[4:5], v[158:159], 0, v[10:11]
	v_lshl_add_u64 v[14:15], v[158:159], 0, v[18:19]
	v_or_b32_e32 v24, v24, v110
	v_mov_b32_e32 v25, v22
	v_or_b32_e32 v48, v48, v110
	v_mov_b32_e32 v49, v30
	global_load_dwordx4 v[4:7], v[4:5], off nt
	v_lshl_add_u64 v[10:11], v[164:165], 0, v[10:11]
	global_load_dwordx4 v[14:17], v[14:15], off nt
	v_lshl_add_u64 v[18:19], v[164:165], 0, v[18:19]
	v_lshlrev_b64 v[26:27], 1, v[24:25]
	v_lshlrev_b64 v[30:31], 1, v[48:49]
	global_load_dwordx4 v[10:13], v[10:11], off nt
	v_lshl_add_u64 v[22:23], v[158:159], 0, v[26:27]
	global_load_dwordx4 v[18:21], v[18:19], off nt
	v_lshl_add_u64 v[48:49], v[164:165], 0, v[30:31]
	v_lshl_add_u64 v[30:31], v[158:159], 0, v[30:31]
	global_load_dwordx4 v[22:25], v[22:23], off nt
	v_lshl_add_u64 v[26:27], v[164:165], 0, v[26:27]
	global_load_dwordx4 v[48:51], v[48:49], off nt
	v_add_u32_e32 v9, v163, v169
	global_load_dwordx4 v[52:55], v[30:31], off nt
	v_add_u32_e32 v30, v168, v169
	global_load_dwordx4 v[26:29], v[26:27], off nt
	v_add_u32_e32 v31, v163, v170
	ds_write_b128 v9, v[32:35]
	s_waitcnt vmcnt(8)
	ds_write_b128 v30, v[96:99]
	ds_write_b128 v31, v[36:39]
	v_add_u32_e32 v31, v168, v170
	ds_write_b128 v31, v[100:103]
	ds_write_b128 v9, v[40:43] offset:18432
	ds_write_b128 v30, v[104:107] offset:18432
	v_add_u32_e32 v31, v163, v171
	ds_write_b128 v31, v[44:47]
	v_add_u32_e32 v31, v168, v171
	v_mov_b32_e32 v155, v8
	v_mov_b32_e32 v151, v8
	ds_write_b128 v31, v[0:3]
	s_waitcnt vmcnt(7)
	ds_write_b128 v9, v[4:7] offset:36864
	s_waitcnt vmcnt(5)
	ds_write_b128 v30, v[10:13] offset:36864
	v_add_u32_e32 v0, v163, v172
	ds_write_b128 v0, v[14:17]
	v_add_u32_e32 v0, v168, v172
	s_waitcnt vmcnt(4)
	ds_write_b128 v0, v[18:21]
	s_waitcnt vmcnt(3)
	ds_write_b128 v9, v[22:25] offset:55296
	s_waitcnt vmcnt(0)
	ds_write_b128 v30, v[26:29] offset:55296
	v_add_u32_e32 v0, v163, v173
	ds_write_b128 v0, v[52:55]
	v_add_u32_e32 v0, v168, v173
	ds_write_b128 v0, v[48:51]
	v_lshl_add_u32 v0, v149, 7, v174
	v_mov_b32_e32 v1, v8
	v_lshlrev_b64 v[0:1], v147, v[0:1]
	v_lshl_add_u64 v[4:5], v[0:1], 0, v[154:155]
	v_mov_b64_e32 v[0:1], s[96:97]
	v_mad_u64_u32 v[0:1], s[14:15], v4, s20, v[0:1]
	v_mov_b32_e32 v2, v1
	v_mad_u64_u32 v[2:3], s[14:15], v5, s20, v[2:3]
	v_mov_b32_e32 v1, v2
	v_lshl_add_u64 v[0:1], v[152:153], 1, v[0:1]
	v_mov_b32_e32 v147, v8
	v_lshl_add_u64 v[0:1], v[0:1], 0, v[146:147]
	s_mov_b64 s[14:15], 0x1200
	v_lshl_add_u64 v[6:7], v[0:1], 0, s[14:15]
	s_movk_i32 s14, 0x1000
	v_add_co_u32_e32 v0, vcc, s14, v0
	s_waitcnt lgkmcnt(0)
	s_nop 0
	v_addc_co_u32_e32 v1, vcc, 0, v1, vcc
	s_barrier
	global_load_dwordx4 v[0:3], v[0:1], off offset:512
	s_nop 0
	global_load_dwordx4 v[10:13], v[6:7], off offset:64
	global_load_dwordx4 v[14:17], v[6:7], off offset:128
	global_load_dwordx4 v[18:21], v[6:7], off offset:192
	ds_read_b128 v[24:27], v215
	ds_read_b128 v[28:31], v215 offset:4608
	ds_read_b128 v[32:35], v215 offset:9216
	ds_read_b128 v[36:39], v215 offset:13824
	ds_read_b128 v[40:43], v215 offset:18432
	ds_read_b128 v[44:47], v215 offset:23040
	ds_read_b128 v[48:51], v215 offset:27648
	ds_read_b128 v[52:55], v215 offset:32256
	ds_read_b128 v[56:59], v215 offset:36864
	ds_read_b128 v[60:63], v215 offset:64
	ds_read_b128 v[64:67], v215 offset:4672
	ds_read_b128 v[68:71], v215 offset:9280
	ds_read_b128 v[72:75], v215 offset:13888
	ds_read_b128 v[76:79], v215 offset:18496
	ds_read_b128 v[80:83], v215 offset:23104
	ds_read_b128 v[84:87], v215 offset:27712
	ds_read_b128 v[88:91], v215 offset:32320
	ds_read_b128 v[92:95], v215 offset:36928
	v_mov_b32_e32 v149, v8
	v_lshlrev_b64 v[6:7], 14, v[148:149]
	v_lshl_add_u64 v[4:5], v[4:5], 0, v[6:7]
	v_lshlrev_b64 v[6:7], 9, v[4:5]
	v_lshl_add_u64 v[6:7], s[0:1], 0, v[6:7]
	v_lshl_add_u64 v[22:23], v[6:7], 0, v[150:151]
	s_waitcnt vmcnt(3) lgkmcnt(14)
	v_mfma_f32_16x16x32_bf16 v[24:27], v[24:27], v[0:3], 0
	v_mfma_f32_16x16x32_bf16 v[28:31], v[28:31], v[0:3], 0
	v_mfma_f32_16x16x32_bf16 v[32:35], v[32:35], v[0:3], 0
	v_mfma_f32_16x16x32_bf16 v[36:39], v[36:39], v[0:3], 0
	s_waitcnt lgkmcnt(13)
	v_mfma_f32_16x16x32_bf16 v[40:43], v[40:43], v[0:3], 0
	s_waitcnt lgkmcnt(12)
	v_mfma_f32_16x16x32_bf16 v[44:47], v[44:47], v[0:3], 0
	s_waitcnt lgkmcnt(11)
	v_mfma_f32_16x16x32_bf16 v[48:51], v[48:51], v[0:3], 0
	s_waitcnt lgkmcnt(10)
	v_mfma_f32_16x16x32_bf16 v[52:55], v[52:55], v[0:3], 0
	s_waitcnt lgkmcnt(9)
; #define LAS __attribute__((address_space(3)))
; template <int DH, bool IS_A> ...
;     ...
;     for (int ks = 0; ks < NKS; ++ks) {
;         if (ks + 1 < NKS) {
; #pragma unroll
;             for (int T = 0; T < 9; ++T) kf[(ks + 1) & 1][T] = *(const LAS bf16x8*)(kp + T * 16 * KS + (ks + 1) * 64); }
;         __builtin_amdgcn_sched_barrier(0);
; #pragma unroll
;         for (int T = 0; T < 9; ++T) s[T] = __builtin_amdgcn_mfma_f32_16x16x32_bf16(kf[ks & 1][T], qf[ks], s[T], 0, 0, 0);
;         __builtin_amdgcn_sched_barrier(0);
;     }
;     const int i = i0 + c16; const int jmin = max(i + (IS_A ? 1 : 0), jlo), jmax = i + 128;
;     float mx = -INFINITY;
; #pragma unroll
;     for (int T = 0; T < 9; ++T)
; #pragma unroll
;         for (int r = 0; r < 4; ++r) { const int j = i0 + 16 * T + 4 * g + r; const bool ok = (j >= jmin) && (j <= jmax); const float v = ok ? s[T][r] : -INFINITY; s[T][r] = v; mx = fmaxf(mx, v); }
	v_mfma_f32_16x16x32_bf16 v[0:3], v[56:59], v[0:3], 0
	ds_read_b128 v[56:59], v215 offset:4736
	ds_read_b128 v[96:99], v215 offset:9344
	ds_read_b128 v[100:103], v215 offset:13952
	ds_read_b128 v[104:107], v215 offset:18560
	ds_read_b128 v[148:151], v215 offset:23168
	ds_read_b128 v[152:155], v215 offset:27776
	ds_read_b128 v[164:167], v215 offset:32384
	ds_read_b128 v[224:227], v215 offset:128
	ds_read_b128 v[228:231], v215 offset:36992
	s_waitcnt vmcnt(2) lgkmcnt(14)
	v_mfma_f32_16x16x32_bf16 v[24:27], v[60:63], v[10:13], v[24:27]
	v_mfma_f32_16x16x32_bf16 v[28:31], v[64:67], v[10:13], v[28:31]
	v_mfma_f32_16x16x32_bf16 v[32:35], v[68:71], v[10:13], v[32:35]
	v_mfma_f32_16x16x32_bf16 v[36:39], v[72:75], v[10:13], v[36:39]
	s_waitcnt lgkmcnt(13)
	v_mfma_f32_16x16x32_bf16 v[40:43], v[76:79], v[10:13], v[40:43]
	s_waitcnt lgkmcnt(12)
	v_mfma_f32_16x16x32_bf16 v[44:47], v[80:83], v[10:13], v[44:47]
	s_waitcnt lgkmcnt(11)
	v_mfma_f32_16x16x32_bf16 v[48:51], v[84:87], v[10:13], v[48:51]
	s_waitcnt lgkmcnt(10)
	v_mfma_f32_16x16x32_bf16 v[52:55], v[88:91], v[10:13], v[52:55]
	s_waitcnt lgkmcnt(9)
	v_mfma_f32_16x16x32_bf16 v[0:3], v[92:95], v[10:13], v[0:3]
	ds_read_b128 v[10:13], v215 offset:4800
	ds_read_b128 v[60:63], v215 offset:9408
	ds_read_b128 v[64:67], v215 offset:14016
	ds_read_b128 v[68:71], v215 offset:18624
	ds_read_b128 v[72:75], v215 offset:23232
	ds_read_b128 v[76:79], v215 offset:27840
	ds_read_b128 v[80:83], v215 offset:32448
	ds_read_b128 v[84:87], v215 offset:192
	ds_read_b128 v[88:91], v215 offset:37056
	s_waitcnt vmcnt(1) lgkmcnt(10)
	v_mfma_f32_16x16x32_bf16 v[24:27], v[224:227], v[14:17], v[24:27]
	v_mfma_f32_16x16x32_bf16 v[28:31], v[56:59], v[14:17], v[28:31]
	v_mfma_f32_16x16x32_bf16 v[32:35], v[96:99], v[14:17], v[32:35]
	v_mfma_f32_16x16x32_bf16 v[36:39], v[100:103], v[14:17], v[36:39]
	v_mfma_f32_16x16x32_bf16 v[40:43], v[104:107], v[14:17], v[40:43]
	v_mfma_f32_16x16x32_bf16 v[44:47], v[148:151], v[14:17], v[44:47]
	v_mfma_f32_16x16x32_bf16 v[48:51], v[152:155], v[14:17], v[48:51]
	v_mfma_f32_16x16x32_bf16 v[52:55], v[164:167], v[14:17], v[52:55]
	s_waitcnt lgkmcnt(9)
	v_mfma_f32_16x16x32_bf16 v[0:3], v[228:231], v[14:17], v[0:3]
	s_waitcnt vmcnt(0) lgkmcnt(1)
	v_mfma_f32_16x16x32_bf16 v[14:17], v[84:87], v[18:21], v[24:27]
	v_mfma_f32_16x16x32_bf16 v[24:27], v[60:63], v[18:21], v[32:35]
	v_mfma_f32_16x16x32_bf16 v[10:13], v[10:13], v[18:21], v[28:31]
	v_mfma_f32_16x16x32_bf16 v[28:31], v[64:67], v[18:21], v[36:39]
	v_mfma_f32_16x16x32_bf16 v[32:35], v[68:71], v[18:21], v[40:43]
	v_mfma_f32_16x16x32_bf16 v[36:39], v[72:75], v[18:21], v[44:47]
	v_mfma_f32_16x16x32_bf16 v[40:43], v[76:79], v[18:21], v[48:51]
	v_mfma_f32_16x16x32_bf16 v[44:47], v[80:83], v[18:21], v[52:55]
	s_waitcnt lgkmcnt(0)
	v_mfma_f32_16x16x32_bf16 v[0:3], v[88:91], v[18:21], v[0:3]
	v_max_i32_e32 v6, v174, v223
	v_readlane_b32 s14, v242, 14
	v_cmp_ge_u32_e32 vcc, v175, v6
	v_readlane_b32 s15, v242, 15
	s_and_b64 vcc, vcc, s[14:15]
	v_readlane_b32 s14, v242, 16
	v_cndmask_b32_e32 v7, v220, v14, vcc
	v_cmp_ge_u32_e32 vcc, v176, v6
	v_readlane_b32 s15, v242, 17
	s_and_b64 vcc, vcc, s[14:15]
	v_readlane_b32 s14, v242, 18
	v_cndmask_b32_e32 v9, v220, v15, vcc
	v_cmp_ge_u32_e32 vcc, v177, v6
	v_readlane_b32 s15, v242, 19
	s_and_b64 vcc, vcc, s[14:15]
	v_readlane_b32 s14, v242, 20
	v_cndmask_b32_e32 v15, v220, v16, vcc
	v_cmp_ge_u32_e32 vcc, v178, v6
	v_readlane_b32 s15, v242, 21
	s_and_b64 vcc, vcc, s[14:15]
	v_readlane_b32 s14, v242, 22
	v_cndmask_b32_e32 v16, v220, v17, vcc
	v_cmp_ge_u32_e32 vcc, v179, v6
	v_readlane_b32 s15, v242, 23
	s_and_b64 vcc, vcc, s[14:15]
	v_readlane_b32 s14, v242, 24
	v_cndmask_b32_e32 v10, v220, v10, vcc
	v_cmp_ge_u32_e32 vcc, v180, v6
	v_readlane_b32 s15, v242, 25
	s_and_b64 vcc, vcc, s[14:15]
	v_readlane_b32 s14, v242, 26
	v_cndmask_b32_e32 v11, v220, v11, vcc
	v_cmp_ge_u32_e32 vcc, v181, v6
	v_readlane_b32 s15, v242, 27
	s_and_b64 vcc, vcc, s[14:15]
	v_readlane_b32 s14, v242, 28
	v_cndmask_b32_e32 v12, v220, v12, vcc
	v_cmp_ge_u32_e32 vcc, v182, v6
	v_readlane_b32 s15, v242, 29
	s_and_b64 vcc, vcc, s[14:15]
	v_readlane_b32 s14, v242, 30
	v_cndmask_b32_e32 v13, v220, v13, vcc
	v_cmp_ge_u32_e32 vcc, v183, v6
	v_readlane_b32 s15, v242, 31
	s_and_b64 vcc, vcc, s[14:15]
	v_readlane_b32 s14, v242, 32
	v_cndmask_b32_e32 v17, v220, v24, vcc
	v_cmp_ge_u32_e32 vcc, v184, v6
	v_readlane_b32 s15, v242, 33
	s_and_b64 vcc, vcc, s[14:15]
	v_cndmask_b32_e32 v18, v220, v25, vcc
	v_cmp_ge_u32_e32 vcc, v185, v6
	s_and_b64 vcc, vcc, s[28:29]
	v_max3_f32 v14, v7, s21, v9
	v_cndmask_b32_e32 v19, v220, v26, vcc
	v_cmp_ge_u32_e32 vcc, v187, v6
	s_and_b64 vcc, vcc, s[30:31]
	v_max3_f32 v14, v14, v15, v16
	v_cndmask_b32_e32 v20, v220, v27, vcc
	v_cmp_ge_u32_e32 vcc, v188, v6
	s_and_b64 vcc, vcc, s[34:35]
	v_max3_f32 v14, v14, v10, v11
	v_cndmask_b32_e32 v21, v220, v28, vcc
	v_cmp_ge_u32_e32 vcc, v189, v6
	s_and_b64 vcc, vcc, s[36:37]
	v_max3_f32 v14, v14, v12, v13
	v_cndmask_b32_e32 v24, v220, v29, vcc
	v_cmp_ge_u32_e32 vcc, v190, v6
	s_and_b64 vcc, vcc, s[38:39]
	v_max3_f32 v14, v14, v17, v18
	v_cndmask_b32_e32 v26, v220, v30, vcc
	v_cmp_ge_u32_e32 vcc, v191, v6
	s_and_b64 vcc, vcc, s[40:41]
	v_max3_f32 v14, v14, v19, v20
	v_cndmask_b32_e32 v27, v220, v31, vcc
	v_cmp_ge_u32_e32 vcc, v193, v6
	s_and_b64 vcc, vcc, s[42:43]
	v_max3_f32 v14, v14, v21, v24
	v_cndmask_b32_e32 v28, v220, v32, vcc
	v_cmp_ge_u32_e32 vcc, v194, v6
	s_and_b64 vcc, vcc, s[44:45]
	v_max3_f32 v14, v14, v26, v27
	v_cndmask_b32_e32 v29, v220, v33, vcc
	v_cmp_ge_u32_e32 vcc, v195, v6
	s_and_b64 vcc, vcc, s[46:47]
	v_max3_f32 v14, v14, v28, v29
	v_cndmask_b32_e32 v30, v220, v34, vcc
; __device__ __forceinline__ float fast_exp2(float x) { return __builtin_amdgcn_exp2f(x); }
; template <int DH, bool IS_A> ...
;     ...
;         for (int r = 0; r < 4; ++r) { const int j = i0 + 16 * T + 4 * g + r; const bool ok = (j >= jmin) && (j <= jmax); const float v = ok ? s[T][r] : -INFINITY; s[T][r] = v; mx = fmaxf(mx, v); }
;     mx = fmaxf(mx, __shfl_xor(mx, 16)); mx = fmaxf(mx, __shfl_xor(mx, 32));
;     if (IS_A) mx = fmaxf(mx, sink2);
;     float sum = 0.f;
; #pragma unroll
;     for (int T = 0; T < 9; ++T)
; #pragma unroll
;         for (int r = 0; r < 4; ++r) { const float p = fast_exp2(s[T][r] - mx); s[T][r] = p; sum += p; }
;     sum += __shfl_xor(sum, 16); sum += __shfl_xor(sum, 32);
	v_cmp_ge_u32_e32 vcc, v196, v6
	s_and_b64 vcc, vcc, s[48:49]
	v_cndmask_b32_e64 v0, v220, v0, s[76:77]
	v_cndmask_b32_e32 v31, v220, v35, vcc
	v_cmp_ge_u32_e32 vcc, v197, v6
	s_and_b64 vcc, vcc, s[50:51]
	v_max3_f32 v14, v14, v30, v31
	v_cndmask_b32_e32 v32, v220, v36, vcc
	v_cmp_ge_u32_e32 vcc, v198, v6
	s_and_b64 vcc, vcc, s[52:53]
	v_and_b32_e32 v25, 64, v221
	v_cndmask_b32_e32 v33, v220, v37, vcc
	v_cmp_ge_u32_e32 vcc, v199, v6
	s_and_b64 vcc, vcc, s[54:55]
	v_max3_f32 v14, v14, v32, v33
	v_cndmask_b32_e32 v34, v220, v38, vcc
	v_cmp_ge_u32_e32 vcc, v200, v6
	s_and_b64 vcc, vcc, s[56:57]
	v_add_u32_e32 v25, 64, v25
	v_cndmask_b32_e32 v35, v220, v39, vcc
	v_cmp_ge_u32_e32 vcc, v201, v6
	s_and_b64 vcc, vcc, s[58:59]
	v_max3_f32 v14, v14, v34, v35
	v_cndmask_b32_e32 v36, v220, v40, vcc
	v_cmp_ge_u32_e32 vcc, v202, v6
	s_and_b64 vcc, vcc, s[26:27]
	v_lshl_add_u64 v[22:23], v[22:23], 0, v[128:129]
	v_cndmask_b32_e32 v37, v220, v41, vcc
	v_cmp_ge_u32_e32 vcc, v203, v6
	s_and_b64 vcc, vcc, s[62:63]
	v_max3_f32 v14, v14, v36, v37
	v_cndmask_b32_e32 v38, v220, v42, vcc
	v_cmp_ge_u32_e32 vcc, v204, v6
	s_and_b64 vcc, vcc, s[64:65]
	s_nop 0
	v_cndmask_b32_e32 v39, v220, v43, vcc
	v_cmp_ge_u32_e32 vcc, v205, v6
	s_and_b64 vcc, vcc, s[66:67]
	v_max3_f32 v14, v14, v38, v39
	v_cndmask_b32_e32 v40, v220, v44, vcc
	v_cmp_ge_u32_e32 vcc, v206, v6
	s_and_b64 vcc, vcc, s[68:69]
	s_nop 0
	v_cndmask_b32_e32 v41, v220, v45, vcc
	v_cmp_ge_u32_e32 vcc, v207, v6
	s_and_b64 vcc, vcc, s[24:25]
	v_max3_f32 v14, v14, v40, v41
	v_cndmask_b32_e32 v42, v220, v46, vcc
	v_cmp_ge_u32_e32 vcc, v208, v6
	s_and_b64 vcc, vcc, s[72:73]
	s_nop 0
	v_cndmask_b32_e32 v43, v220, v47, vcc
	v_cmp_ge_u32_e32 vcc, v209, v6
	s_and_b64 vcc, vcc, s[78:79]
	v_max3_f32 v14, v14, v42, v43
	v_cndmask_b32_e32 v1, v220, v1, vcc
	v_cmp_ge_u32_e32 vcc, v210, v6
	s_and_b64 vcc, vcc, s[80:81]
	v_max3_f32 v14, v14, v0, v1
	v_cndmask_b32_e32 v2, v220, v2, vcc
	v_cmp_ge_u32_e32 vcc, v211, v6
	s_and_b64 vcc, vcc, s[82:83]
	s_nop 0
	v_cndmask_b32_e32 v3, v220, v3, vcc
	v_max3_f32 v6, v14, v2, v3
	v_xor_b32_e32 v14, 16, v221
	v_cmp_lt_i32_e32 vcc, v14, v25
	s_nop 1
	v_cndmask_b32_e32 v14, v221, v14, vcc
	v_lshlrev_b32_e32 v14, 2, v14
	ds_bpermute_b32 v44, v14, v6
	s_waitcnt lgkmcnt(0)
	v_max_f32_e32 v44, v44, v44
	v_max_f32_e32 v6, v6, v44
	v_xor_b32_e32 v44, 32, v221
	v_cmp_lt_i32_e32 vcc, v44, v25
	s_nop 1
	v_cndmask_b32_e32 v25, v221, v44, vcc
	v_lshlrev_b32_e32 v44, 2, v25
	ds_bpermute_b32 v25, v44, v6
	s_waitcnt lgkmcnt(0)
	v_max_f32_e32 v25, v25, v25
	v_max_f32_e32 v25, v6, v25
	v_sub_f32_e32 v6, v7, v25
	v_exp_f32_e32 v6, v6
	v_sub_f32_e32 v9, v9, v25
	v_exp_f32_e32 v9, v9
	v_sub_f32_e32 v15, v15, v25
	v_exp_f32_e32 v15, v15
	v_sub_f32_e32 v16, v16, v25
	v_exp_f32_e32 v16, v16
	v_sub_f32_e32 v10, v10, v25
	v_add_f32_e32 v7, 0, v6
	v_exp_f32_e32 v10, v10
	v_sub_f32_e32 v11, v11, v25
	v_add_f32_e32 v7, v9, v7
	v_exp_f32_e32 v11, v11
	v_sub_f32_e32 v12, v12, v25
	v_add_f32_e32 v7, v15, v7
	v_exp_f32_e32 v12, v12
	v_sub_f32_e32 v13, v13, v25
	v_add_f32_e32 v7, v16, v7
	v_exp_f32_e32 v13, v13
	v_sub_f32_e32 v17, v17, v25
	v_add_f32_e32 v7, v10, v7
	v_exp_f32_e32 v17, v17
	v_sub_f32_e32 v18, v18, v25
	v_add_f32_e32 v7, v11, v7
	v_exp_f32_e32 v18, v18
	v_sub_f32_e32 v19, v19, v25
	v_add_f32_e32 v7, v12, v7
	v_exp_f32_e32 v19, v19
	v_sub_f32_e32 v20, v20, v25
	v_add_f32_e32 v7, v13, v7
	v_exp_f32_e32 v20, v20
	v_sub_f32_e32 v21, v21, v25
	v_add_f32_e32 v7, v17, v7
	v_exp_f32_e32 v21, v21
	v_sub_f32_e32 v24, v24, v25
	v_add_f32_e32 v7, v18, v7
	v_exp_f32_e32 v24, v24
	v_sub_f32_e32 v26, v26, v25
	v_add_f32_e32 v7, v19, v7
	v_exp_f32_e32 v26, v26
	v_sub_f32_e32 v27, v27, v25
	v_add_f32_e32 v7, v20, v7
	v_exp_f32_e32 v27, v27
	v_sub_f32_e32 v28, v28, v25
	v_add_f32_e32 v7, v21, v7
	v_exp_f32_e32 v28, v28
	v_sub_f32_e32 v29, v29, v25
	v_add_f32_e32 v7, v24, v7
	v_exp_f32_e32 v29, v29
	v_sub_f32_e32 v30, v30, v25
	v_add_f32_e32 v7, v26, v7
	v_exp_f32_e32 v30, v30
	v_sub_f32_e32 v31, v31, v25
	v_add_f32_e32 v7, v27, v7
	v_exp_f32_e32 v31, v31
	v_sub_f32_e32 v32, v32, v25
	v_add_f32_e32 v7, v28, v7
	v_exp_f32_e32 v32, v32
	v_sub_f32_e32 v33, v33, v25
	v_add_f32_e32 v7, v29, v7
	v_exp_f32_e32 v33, v33
	v_sub_f32_e32 v34, v34, v25
	v_add_f32_e32 v7, v30, v7
	v_exp_f32_e32 v34, v34
	v_sub_f32_e32 v35, v35, v25
	v_add_f32_e32 v7, v31, v7
	v_exp_f32_e32 v35, v35
	v_sub_f32_e32 v36, v36, v25
	v_add_f32_e32 v7, v32, v7
	v_exp_f32_e32 v36, v36
	v_sub_f32_e32 v37, v37, v25
	v_add_f32_e32 v7, v33, v7
	v_exp_f32_e32 v37, v37
	v_sub_f32_e32 v38, v38, v25
	v_add_f32_e32 v7, v34, v7
	v_exp_f32_e32 v38, v38
	v_sub_f32_e32 v39, v39, v25
	v_add_f32_e32 v7, v35, v7
	v_exp_f32_e32 v39, v39
	v_sub_f32_e32 v40, v40, v25
	v_add_f32_e32 v7, v36, v7
	v_exp_f32_e32 v40, v40
	v_sub_f32_e32 v41, v41, v25
	v_add_f32_e32 v7, v37, v7
	v_exp_f32_e32 v41, v41
	v_sub_f32_e32 v42, v42, v25
	v_add_f32_e32 v7, v38, v7
	v_exp_f32_e32 v42, v42
	v_sub_f32_e32 v43, v43, v25
	v_add_f32_e32 v7, v39, v7
	v_exp_f32_e32 v43, v43
	v_sub_f32_e32 v0, v0, v25
	v_add_f32_e32 v7, v40, v7
	v_exp_f32_e32 v45, v0
	v_add_f32_e32 v7, v41, v7
	v_add_f32_e32 v7, v42, v7
	v_add_f32_e32 v7, v43, v7
	v_sub_f32_e32 v1, v1, v25
	v_add_f32_e32 v0, v45, v7
	v_exp_f32_e32 v7, v1
	v_sub_f32_e32 v1, v2, v25
	v_exp_f32_e32 v46, v1
	v_sub_f32_e32 v1, v3, v25
	v_exp_f32_e32 v47, v1
	v_add_f32_e32 v0, v7, v0
	v_add_f32_e32 v0, v46, v0
	v_add_f32_e32 v0, v47, v0
	ds_bpermute_b32 v1, v14, v0
	s_waitcnt lgkmcnt(0)
; #define LAS __attribute__((address_space(3)))
; template <int DH, bool IS_A> ...
;     ...
;     sum += __shfl_xor(sum, 16); sum += __shfl_xor(sum, 32);
;     if (IS_A) sum += fast_exp2(sink2 - mx);
;     bf16x8 pf[4];
; #pragma unroll
;     for (int k = 0; k < 4; ++k) { u32x4 w; w.x = cvt_pk_bf16(s[2 * k][0], s[2 * k][1]); w.y = cvt_pk_bf16(s[2 * k][2], s[2 * k][3]); w.z = cvt_pk_bf16(s[2 * k + 1][0], s[2 * k + 1][1]); w.w = cvt_pk_bf16(s[2 * k + 1][2], s[2 * k + 1][3]);
;         pf[k] = __builtin_bit_cast(bf16x8, w); }
;     bf16x4 p8; { u32x2 w; w.x = cvt_pk_bf16(s[8][0], s[8][1]); w.y = cvt_pk_bf16(s[8][2], s[8][3]); p8 = __builtin_bit_cast(bf16x4, w); }
;     const int q4 = c16 >> 2, p4 = c16 & 3;
;     const LAS unsigned char* vp = Vl + (i0 + 4 * g + q4) * VS + 8 * p4;
;     const float inv = fast_rcp(sum);
;     bf16x4 vv[2][9];
; #pragma unroll
;     for (int r9 = 0; r9 < 9; ++r9) vv[0][r9] = __builtin_amdgcn_ds_read_tr16_b64_v4i16((LAS bf16x4*)(vp + (16 * r9) * VS));
; #pragma unroll
;     for (int dt = 0; dt < NDT; ++dt) {
;         if (dt + 1 < NDT) {
; #pragma unroll
;             for (int r9 = 0; r9 < 9; ++r9) vv[(dt + 1) & 1][r9] = __builtin_amdgcn_ds_read_tr16_b64_v4i16((LAS bf16x4*)(vp + (16 * r9) * VS + (dt + 1) * 32)); }
;         __builtin_amdgcn_sched_barrier(0);
;         f32x4 o = (f32x4){0.f, 0.f, 0.f, 0.f};
; #pragma unroll
;         for (int k = 0; k < 4; ++k) {
;             const bf16x4 lo = vv[dt & 1][2 * k], hi = vv[dt & 1][2 * k + 1];
;             o = __builtin_amdgcn_mfma_f32_16x16x32_bf16((bf16x8){lo[0], lo[1], lo[2], lo[3], hi[0], hi[1], hi[2], hi[3]}, pf[k], o, 0, 0, 0);
;         }
;         { const bf16x4 l8 = vv[dt & 1][8];
;           o = __builtin_amdgcn_mfma_f32_16x16x32_bf16((bf16x8){l8[0], l8[1], l8[2], l8[3], l8[0], l8[1], l8[2], l8[3]}, (bf16x8){p8[0], p8[1], p8[2], p8[3], 0, 0, 0, 0}, o, 0, 0, 0); }
;         __builtin_amdgcn_sched_barrier(0);
;         o = o * inv;
;         if (IS_A) { typedef float f2 __attribute__((ext_vector_type(2))); const f2 ga = __builtin_amdgcn_cvt_pk_f32_fp8((int)gwv[dt].x, false), gb = __builtin_amdgcn_cvt_pk_f32_fp8((int)gwv[dt].x, true);
;             o[0] *= ga[0] * SU8; o[1] *= ga[1] * SU8; o[2] *= gb[0] * SU8; o[3] *= gb[1] * SU8;
;             *(unsigned*)(u8row + 16 * dt + 4 * g) = pack_fp8x4(o[0], o[1], o[2], o[3]); }
	v_add_f32_e32 v48, v0, v1
	ds_bpermute_b32 v49, v44, v48
	v_cvt_pk_bf16_f32 v0, v6, v9
	v_cvt_pk_bf16_f32 v1, v15, v16
	v_cvt_pk_bf16_f32 v2, v10, v11
	v_cvt_pk_bf16_f32 v3, v12, v13
	v_cvt_pk_bf16_f32 v10, v17, v18
	v_cvt_pk_bf16_f32 v11, v19, v20
	v_cvt_pk_bf16_f32 v12, v21, v24
	v_cvt_pk_bf16_f32 v13, v26, v27
	v_cvt_pk_bf16_f32 v14, v28, v29
	v_cvt_pk_bf16_f32 v15, v30, v31
	v_cvt_pk_bf16_f32 v16, v32, v33
	v_cvt_pk_bf16_f32 v17, v34, v35
	v_cvt_pk_bf16_f32 v18, v36, v37
	v_cvt_pk_bf16_f32 v19, v38, v39
	v_cvt_pk_bf16_f32 v20, v40, v41
	v_cvt_pk_bf16_f32 v21, v42, v43
	v_cvt_pk_bf16_f32 v6, v45, v7
	v_cvt_pk_bf16_f32 v7, v46, v47
	ds_read_b64_tr_b16 v[30:31], v212 offset:4608
	ds_read_b64_tr_b16 v[32:33], v212 offset:9216
	ds_read_b64_tr_b16 v[34:35], v212 offset:13824
	ds_read_b64_tr_b16 v[36:37], v212 offset:18432
	ds_read_b64_tr_b16 v[38:39], v212 offset:23040
	ds_read_b64_tr_b16 v[40:41], v212 offset:27648
	ds_read_b64_tr_b16 v[42:43], v212 offset:32256
	ds_read_b64_tr_b16 v[44:45], v212 offset:36864
	s_waitcnt lgkmcnt(8)
	v_add_f32_e32 v26, v48, v49
	ds_read_b64_tr_b16 v[28:29], v212
	ds_read_b64_tr_b16 v[48:49], v212 offset:32
	ds_read_b64_tr_b16 v[50:51], v212 offset:4640
	ds_read_b64_tr_b16 v[52:53], v212 offset:9248
	ds_read_b64_tr_b16 v[54:55], v212 offset:13856
	ds_read_b64_tr_b16 v[56:57], v212 offset:18464
	ds_read_b64_tr_b16 v[58:59], v212 offset:23072
	ds_read_b64_tr_b16 v[60:61], v212 offset:27680
	ds_read_b64_tr_b16 v[62:63], v212 offset:32288
	ds_read_b64_tr_b16 v[64:65], v212 offset:36896
	v_rcp_f32_e32 v24, v26
	v_mov_b32_e32 v9, v8
	s_waitcnt lgkmcnt(9)
	v_mfma_f32_16x16x32_bf16 v[28:31], v[28:31], v[0:3], 0
	v_mov_b32_e32 v46, v44
	v_mov_b32_e32 v47, v45
	v_mfma_f32_16x16x32_bf16 v[28:31], v[32:35], v[10:13], v[28:31]
	v_mfma_f32_16x16x32_bf16 v[28:31], v[36:39], v[14:17], v[28:31]
	v_mfma_f32_16x16x32_bf16 v[28:31], v[40:43], v[18:21], v[28:31]
	v_mfma_f32_16x16x32_bf16 v[28:31], v[44:47], v[6:9], v[28:31]
	s_nop 7
	v_pk_mul_f32 v[30:31], v[30:31], v[24:25] op_sel_hi:[1,0]
	v_pk_mul_f32 v[28:29], v[28:29], v[24:25] op_sel_hi:[1,0]
	s_nop 0
	v_mul_f32_e32 v27, 0x41800000, v28
	v_mul_f32_e32 v28, 0x41800000, v29
	v_mul_f32_e32 v29, 0x41800000, v30
	v_mul_f32_e32 v30, 0x41800000, v31
	v_mov_b32_e32 v31, v8
	v_cvt_pk_fp8_f32 v31, v27, v28
	v_mov_b32_e32 v27, v8
	v_cvt_pk_fp8_f32 v27, v29, v30
	v_and_b32_e32 v28, 0xffff, v31
	v_lshl_or_b32 v27, v27, 16, v28
	global_store_dword v[22:23], v27, off
	ds_read_b64_tr_b16 v[28:29], v212 offset:64
	ds_read_b64_tr_b16 v[30:31], v212 offset:4672
	ds_read_b64_tr_b16 v[32:33], v212 offset:9280
	ds_read_b64_tr_b16 v[34:35], v212 offset:13888
	ds_read_b64_tr_b16 v[36:37], v212 offset:18496
	ds_read_b64_tr_b16 v[38:39], v212 offset:23104
	ds_read_b64_tr_b16 v[40:41], v212 offset:27712
	ds_read_b64_tr_b16 v[42:43], v212 offset:32320
	ds_read_b64_tr_b16 v[44:45], v212 offset:36928
	s_waitcnt lgkmcnt(14)
	v_mfma_f32_16x16x32_bf16 v[46:49], v[48:51], v[0:3], 0
	s_waitcnt lgkmcnt(9)
	v_mov_b32_e32 v66, v64
	v_mov_b32_e32 v67, v65
	v_mfma_f32_16x16x32_bf16 v[46:49], v[52:55], v[10:13], v[46:49]
	v_mfma_f32_16x16x32_bf16 v[46:49], v[56:59], v[14:17], v[46:49]
	v_mfma_f32_16x16x32_bf16 v[46:49], v[60:63], v[18:21], v[46:49]
	v_mfma_f32_16x16x32_bf16 v[46:49], v[64:67], v[6:9], v[46:49]
	s_nop 7
	v_pk_mul_f32 v[48:49], v[48:49], v[24:25] op_sel_hi:[1,0]
	v_pk_mul_f32 v[46:47], v[46:47], v[24:25] op_sel_hi:[1,0]
	s_nop 0
	v_mul_f32_e32 v27, 0x41800000, v46
	v_mul_f32_e32 v46, 0x41800000, v47
	v_mul_f32_e32 v47, 0x41800000, v48
	v_mul_f32_e32 v48, 0x41800000, v49
	v_mov_b32_e32 v49, v8
	v_cvt_pk_fp8_f32 v49, v27, v46
	v_mov_b32_e32 v27, v8
	v_cvt_pk_fp8_f32 v27, v47, v48
	v_and_b32_e32 v46, 0xffff, v49
	v_lshl_or_b32 v27, v27, 16, v46
	global_store_dword v[22:23], v27, off offset:16
	ds_read_b64_tr_b16 v[48:49], v212 offset:96
	ds_read_b64_tr_b16 v[50:51], v212 offset:4704
	ds_read_b64_tr_b16 v[52:53], v212 offset:9312
	ds_read_b64_tr_b16 v[54:55], v212 offset:13920
	ds_read_b64_tr_b16 v[56:57], v212 offset:18528
	ds_read_b64_tr_b16 v[58:59], v212 offset:23136
	ds_read_b64_tr_b16 v[60:61], v212 offset:27744
	ds_read_b64_tr_b16 v[62:63], v212 offset:32352
	ds_read_b64_tr_b16 v[64:65], v212 offset:36960
	s_waitcnt lgkmcnt(14)
	v_mfma_f32_16x16x32_bf16 v[28:31], v[28:31], v[0:3], 0
	s_waitcnt lgkmcnt(9)
	v_mov_b32_e32 v46, v44
	v_mov_b32_e32 v47, v45
	v_mfma_f32_16x16x32_bf16 v[28:31], v[32:35], v[10:13], v[28:31]
	v_mfma_f32_16x16x32_bf16 v[28:31], v[36:39], v[14:17], v[28:31]
	v_mfma_f32_16x16x32_bf16 v[28:31], v[40:43], v[18:21], v[28:31]
	v_mfma_f32_16x16x32_bf16 v[28:31], v[44:47], v[6:9], v[28:31]
	s_nop 7
	v_pk_mul_f32 v[30:31], v[24:25], v[30:31] op_sel_hi:[0,1]
	v_pk_mul_f32 v[28:29], v[24:25], v[28:29] op_sel_hi:[0,1]
	v_mul_f32_e32 v27, 0x41800000, v28
	v_mul_f32_e32 v28, 0x41800000, v29
	v_mul_f32_e32 v29, 0x41800000, v30
	v_mul_f32_e32 v30, 0x41800000, v31
	v_mov_b32_e32 v31, v8
	v_cvt_pk_fp8_f32 v31, v27, v28
	v_mov_b32_e32 v27, v8
	v_cvt_pk_fp8_f32 v27, v29, v30
	v_and_b32_e32 v28, 0xffff, v31
	v_lshl_or_b32 v27, v27, 16, v28
	global_store_dword v[22:23], v27, off offset:32
	ds_read_b64_tr_b16 v[28:29], v212 offset:128
	ds_read_b64_tr_b16 v[30:31], v212 offset:4736
	ds_read_b64_tr_b16 v[32:33], v212 offset:9344
	ds_read_b64_tr_b16 v[34:35], v212 offset:13952
	ds_read_b64_tr_b16 v[36:37], v212 offset:18560
	ds_read_b64_tr_b16 v[38:39], v212 offset:23168
	ds_read_b64_tr_b16 v[40:41], v212 offset:27776
	ds_read_b64_tr_b16 v[42:43], v212 offset:32384
	ds_read_b64_tr_b16 v[44:45], v212 offset:36992
	s_waitcnt lgkmcnt(14)
	v_mfma_f32_16x16x32_bf16 v[46:49], v[48:51], v[0:3], 0
	s_waitcnt lgkmcnt(9)
; #define LAS __attribute__((address_space(3)))
; template <int DH, bool IS_A> ...
;     ...
;     for (int dt = 0; dt < NDT; ++dt) {
;         if (dt + 1 < NDT) {
; #pragma unroll
;             for (int r9 = 0; r9 < 9; ++r9) vv[(dt + 1) & 1][r9] = __builtin_amdgcn_ds_read_tr16_b64_v4i16((LAS bf16x4*)(vp + (16 * r9) * VS + (dt + 1) * 32)); }
;         __builtin_amdgcn_sched_barrier(0);
;         f32x4 o = (f32x4){0.f, 0.f, 0.f, 0.f};
; #pragma unroll
;         for (int k = 0; k < 4; ++k) {
;             const bf16x4 lo = vv[dt & 1][2 * k], hi = vv[dt & 1][2 * k + 1];
;             o = __builtin_amdgcn_mfma_f32_16x16x32_bf16((bf16x8){lo[0], lo[1], lo[2], lo[3], hi[0], hi[1], hi[2], hi[3]}, pf[k], o, 0, 0, 0);
;         }
;         { const bf16x4 l8 = vv[dt & 1][8];
;           o = __builtin_amdgcn_mfma_f32_16x16x32_bf16((bf16x8){l8[0], l8[1], l8[2], l8[3], l8[0], l8[1], l8[2], l8[3]}, (bf16x8){p8[0], p8[1], p8[2], p8[3], 0, 0, 0, 0}, o, 0, 0, 0); }
;         __builtin_amdgcn_sched_barrier(0);
;         o = o * inv;
;         if (IS_A) { typedef float f2 __attribute__((ext_vector_type(2))); const f2 ga = __builtin_amdgcn_cvt_pk_f32_fp8((int)gwv[dt].x, false), gb = __builtin_amdgcn_cvt_pk_f32_fp8((int)gwv[dt].x, true);
;             o[0] *= ga[0] * SU8; o[1] *= ga[1] * SU8; o[2] *= gb[0] * SU8; o[3] *= gb[1] * SU8;
;             *(unsigned*)(u8row + 16 * dt + 4 * g) = pack_fp8x4(o[0], o[1], o[2], o[3]); }
;         else *(unsigned*)((unsigned char*)orow + 16 * dt + 4 * g) = pack_fp8x4(o[0] * SU8, o[1] * SU8, o[2] * SU8, o[3] * SU8);
;     }
;     if (!IS_A) { if (g == 0) *lse_ptr = mx + __builtin_amdgcn_logf(sum); }
	v_mov_b32_e32 v66, v64
	v_mov_b32_e32 v67, v65
	v_mfma_f32_16x16x32_bf16 v[46:49], v[52:55], v[10:13], v[46:49]
	v_mfma_f32_16x16x32_bf16 v[46:49], v[56:59], v[14:17], v[46:49]
	v_mfma_f32_16x16x32_bf16 v[46:49], v[60:63], v[18:21], v[46:49]
	v_mfma_f32_16x16x32_bf16 v[46:49], v[64:67], v[6:9], v[46:49]
	s_nop 7
	v_pk_mul_f32 v[48:49], v[24:25], v[48:49] op_sel_hi:[0,1]
	v_pk_mul_f32 v[46:47], v[24:25], v[46:47] op_sel_hi:[0,1]
	v_mul_f32_e32 v27, 0x41800000, v46
	v_mul_f32_e32 v46, 0x41800000, v47
	v_mul_f32_e32 v47, 0x41800000, v48
	v_mul_f32_e32 v48, 0x41800000, v49
	v_mov_b32_e32 v49, v8
	v_cvt_pk_fp8_f32 v49, v27, v46
	v_mov_b32_e32 v27, v8
	v_cvt_pk_fp8_f32 v27, v47, v48
	v_and_b32_e32 v46, 0xffff, v49
	v_lshl_or_b32 v27, v27, 16, v46
	global_store_dword v[22:23], v27, off offset:48
	ds_read_b64_tr_b16 v[48:49], v212 offset:160
	ds_read_b64_tr_b16 v[50:51], v212 offset:4768
	ds_read_b64_tr_b16 v[52:53], v212 offset:9376
	ds_read_b64_tr_b16 v[54:55], v212 offset:13984
	ds_read_b64_tr_b16 v[56:57], v212 offset:18592
	ds_read_b64_tr_b16 v[58:59], v212 offset:23200
	ds_read_b64_tr_b16 v[60:61], v212 offset:27808
	ds_read_b64_tr_b16 v[62:63], v212 offset:32416
	ds_read_b64_tr_b16 v[64:65], v212 offset:37024
	s_waitcnt lgkmcnt(14)
	v_mfma_f32_16x16x32_bf16 v[28:31], v[28:31], v[0:3], 0
	s_waitcnt lgkmcnt(9)
	v_mov_b32_e32 v46, v44
	v_mov_b32_e32 v47, v45
	v_mfma_f32_16x16x32_bf16 v[28:31], v[32:35], v[10:13], v[28:31]
	v_mfma_f32_16x16x32_bf16 v[28:31], v[36:39], v[14:17], v[28:31]
	v_mfma_f32_16x16x32_bf16 v[28:31], v[40:43], v[18:21], v[28:31]
	v_mfma_f32_16x16x32_bf16 v[28:31], v[44:47], v[6:9], v[28:31]
	s_nop 7
	v_pk_mul_f32 v[30:31], v[24:25], v[30:31] op_sel_hi:[0,1]
	v_pk_mul_f32 v[28:29], v[24:25], v[28:29] op_sel_hi:[0,1]
	v_mul_f32_e32 v27, 0x41800000, v28
	v_mul_f32_e32 v28, 0x41800000, v29
	v_mul_f32_e32 v29, 0x41800000, v30
	v_mul_f32_e32 v30, 0x41800000, v31
	v_mov_b32_e32 v31, v8
	v_cvt_pk_fp8_f32 v31, v27, v28
	v_mov_b32_e32 v27, v8
	v_cvt_pk_fp8_f32 v27, v29, v30
	v_and_b32_e32 v28, 0xffff, v31
	v_lshl_or_b32 v27, v27, 16, v28
	global_store_dword v[22:23], v27, off offset:64
	ds_read_b64_tr_b16 v[28:29], v212 offset:192
	ds_read_b64_tr_b16 v[30:31], v212 offset:4800
	ds_read_b64_tr_b16 v[32:33], v212 offset:9408
	ds_read_b64_tr_b16 v[34:35], v212 offset:14016
	ds_read_b64_tr_b16 v[36:37], v212 offset:18624
	ds_read_b64_tr_b16 v[38:39], v212 offset:23232
	ds_read_b64_tr_b16 v[40:41], v212 offset:27840
	ds_read_b64_tr_b16 v[42:43], v212 offset:32448
	ds_read_b64_tr_b16 v[44:45], v212 offset:37056
	s_waitcnt lgkmcnt(14)
	v_mfma_f32_16x16x32_bf16 v[46:49], v[48:51], v[0:3], 0
	s_waitcnt lgkmcnt(9)
	v_mov_b32_e32 v66, v64
	v_mov_b32_e32 v67, v65
	v_mfma_f32_16x16x32_bf16 v[46:49], v[52:55], v[10:13], v[46:49]
	v_mfma_f32_16x16x32_bf16 v[46:49], v[56:59], v[14:17], v[46:49]
	v_mfma_f32_16x16x32_bf16 v[46:49], v[60:63], v[18:21], v[46:49]
	v_mfma_f32_16x16x32_bf16 v[46:49], v[64:67], v[6:9], v[46:49]
	s_nop 7
	v_pk_mul_f32 v[48:49], v[24:25], v[48:49] op_sel_hi:[0,1]
	v_pk_mul_f32 v[46:47], v[24:25], v[46:47] op_sel_hi:[0,1]
	v_mul_f32_e32 v27, 0x41800000, v46
	v_mul_f32_e32 v46, 0x41800000, v47
	v_mul_f32_e32 v47, 0x41800000, v48
	v_mul_f32_e32 v48, 0x41800000, v49
	v_mov_b32_e32 v49, v8
	v_cvt_pk_fp8_f32 v49, v27, v46
	v_mov_b32_e32 v27, v8
	v_cvt_pk_fp8_f32 v27, v47, v48
	v_and_b32_e32 v46, 0xffff, v49
	v_lshl_or_b32 v27, v27, 16, v46
	global_store_dword v[22:23], v27, off offset:80
	ds_read_b64_tr_b16 v[48:49], v212 offset:224
	ds_read_b64_tr_b16 v[50:51], v212 offset:4832
	ds_read_b64_tr_b16 v[52:53], v212 offset:9440
	ds_read_b64_tr_b16 v[54:55], v212 offset:14048
	ds_read_b64_tr_b16 v[56:57], v212 offset:18656
	ds_read_b64_tr_b16 v[58:59], v212 offset:23264
	ds_read_b64_tr_b16 v[60:61], v212 offset:27872
	ds_read_b64_tr_b16 v[62:63], v212 offset:32480
	ds_read_b64_tr_b16 v[64:65], v212 offset:37088
	s_waitcnt lgkmcnt(14)
	v_mfma_f32_16x16x32_bf16 v[28:31], v[28:31], v[0:3], 0
	s_waitcnt lgkmcnt(9)
	v_mov_b32_e32 v46, v44
	v_mov_b32_e32 v47, v45
	v_mfma_f32_16x16x32_bf16 v[28:31], v[32:35], v[10:13], v[28:31]
	v_mfma_f32_16x16x32_bf16 v[28:31], v[36:39], v[14:17], v[28:31]
	v_mfma_f32_16x16x32_bf16 v[28:31], v[40:43], v[18:21], v[28:31]
	v_mfma_f32_16x16x32_bf16 v[28:31], v[44:47], v[6:9], v[28:31]
	s_nop 7
	v_pk_mul_f32 v[30:31], v[24:25], v[30:31] op_sel_hi:[0,1]
	v_pk_mul_f32 v[28:29], v[24:25], v[28:29] op_sel_hi:[0,1]
	v_mul_f32_e32 v27, 0x41800000, v28
	v_mul_f32_e32 v28, 0x41800000, v29
	v_mul_f32_e32 v29, 0x41800000, v30
	v_mul_f32_e32 v30, 0x41800000, v31
	v_mov_b32_e32 v31, v8
	v_cvt_pk_fp8_f32 v31, v27, v28
	v_mov_b32_e32 v27, v8
	v_cvt_pk_fp8_f32 v27, v29, v30
	v_and_b32_e32 v28, 0xffff, v31
	v_lshl_or_b32 v27, v27, 16, v28
	global_store_dword v[22:23], v27, off offset:96
	s_waitcnt lgkmcnt(7)
	v_mfma_f32_16x16x32_bf16 v[0:3], v[48:51], v[0:3], 0
	s_waitcnt lgkmcnt(0)
	v_mov_b32_e32 v66, v64
	v_mov_b32_e32 v67, v65
	v_mfma_f32_16x16x32_bf16 v[0:3], v[52:55], v[10:13], v[0:3]
	v_mfma_f32_16x16x32_bf16 v[0:3], v[56:59], v[14:17], v[0:3]
	v_mfma_f32_16x16x32_bf16 v[0:3], v[60:63], v[18:21], v[0:3]
	v_mfma_f32_16x16x32_bf16 v[0:3], v[64:67], v[6:9], v[0:3]
	s_nop 7
	v_pk_mul_f32 v[0:1], v[24:25], v[0:1] op_sel_hi:[0,1]
	v_pk_mul_f32 v[2:3], v[24:25], v[2:3] op_sel_hi:[0,1]
	v_mul_f32_e32 v0, 0x41800000, v0
	v_mul_f32_e32 v1, 0x41800000, v1
	v_mov_b32_e32 v6, v8
	v_mul_f32_e32 v2, 0x41800000, v2
	v_mul_f32_e32 v3, 0x41800000, v3
	v_cvt_pk_fp8_f32 v6, v0, v1
	v_mov_b32_e32 v0, v8
	v_cvt_pk_fp8_f32 v0, v2, v3
	v_and_b32_e32 v1, 0xffff, v6
	v_lshl_or_b32 v0, v0, 16, v1
	global_store_dword v[22:23], v0, off offset:112
	s_and_saveexec_b64 s[14:15], s[84:85]
	s_cbranch_execz .LBB0_327
	v_log_f32_e32 v6, v26
	v_readlane_b32 s16, v242, 6
	v_readlane_b32 s17, v242, 7
	v_lshlrev_b32_e32 v2, 2, v222
	v_mov_b32_e32 v3, v8
	v_lshl_add_u64 v[0:1], v[4:5], 4, s[16:17]
	v_add_f32_e32 v4, v25, v6
	v_lshl_add_u64 v[0:1], v[0:1], 0, v[2:3]
	global_store_dword v[0:1], v4, off
